# epilogues of the one-unit GEMM phases 5/6/7: each 16-row group issues its four rungs' loads together and waits with counts (8 round trips per wave instead of 32, stores no longer drained per rung)
# speedup vs baseline: 1.0202x; 1.0007x over previous
; __device__ __forceinline__ unsigned cvt_pk_bf16(float lo, float hi) { typedef float f2_ __attribute__((ext_vector_type(2))); typedef __bf16 b2_ __attribute__((ext_vector_type(2))); f2_ v = {lo, hi}; b2_ b = __builtin_convertvector(v, b2_); return __builtin_bit_cast(unsigned, b); }
;     DEV void apply(int r, int c, const f32x4 v) const { st_bf16x4(MG + (size_t)r * DM + c, *(const f32x4*)(PT + (size_t)r * DM + c) + v * ld_bf16x4(SG + (size_t)r * DM + c)); }
; DEV f32x4 ld_bf16x4(const bf16* p) { const v2u w = *(const v2u*)p; return (f32x4){bflo(w.x), bfhi(w.x), bflo(w.y), bfhi(w.y)}; }
; DEV void st_bf16x4(bf16* p, const f32x4 v) { v2u w; w.x = pg8::cvt_pk_bf16(v[0], v[1]); w.y = pg8::cvt_pk_bf16(v[2], v[3]); *(v2u*)p = w; }
;     DEV void apply(int r, int c, const f32x4 v) const { *(f32x4*)(PT + (size_t)r * DM + c) = v * ld_bf16x4(SG + (size_t)r * DM + c); }
;     DEV void operator()(const f32x4 (&acc)[2][2][4][2], const pg8::Unit& u, int wr, int wc, int fr_, int fq_) const { int fr = fr_, fq = fq_; asm volatile("" : "+v"(fr), "+v"(fq));
;         EPI_ALL({ apply(r, c, v); }) }
.LBB0_1784:
	s_lshl_b32 s17, s22, 8
	v_mov_b32_e32 v142, v1
	v_mov_b32_e32 v143, v146
	s_add_i32 s17, s17, s42
	s_nop 0
	v_add_u32_e32 v144, s17, v142
	s_lshl_b32 s17, s24, 8
	s_or_b32 s17, s17, s43
	v_lshl_add_u32 v142, v143, 2, s17
	v_cmp_gt_i32_e32 vcc, s54, v144
	v_ashrrev_i32_e32 v143, 31, v142
	s_and_saveexec_b64 s[22:23], vcc
	s_cbranch_execz .LBB0_1786
	v_ashrrev_i32_e32 v145, 31, v144
	v_lshlrev_b64 v[152:153], 11, v[144:145]
	v_lshl_add_u64 v[152:153], s[6:7], 0, v[152:153]
	v_lshl_add_u64 v[152:153], v[142:143], 1, v[152:153]
	global_load_dwordx2 v[154:155], v[152:153], off
	v_lshlrev_b64 v[156:157], 12, v[144:145]
	v_lshl_add_u64 v[156:157], s[8:9], 0, v[156:157]
	v_lshl_add_u64 v[156:157], v[142:143], 2, v[156:157]
	global_load_dwordx2 v[174:175], v[152:153], off offset:32
	global_load_dwordx2 v[176:177], v[152:153], off offset:256
	global_load_dwordx2 v[178:179], v[152:153], off offset:288
	s_waitcnt vmcnt(3)
	v_lshlrev_b32_e32 v170, 16, v154
	v_and_b32_e32 v171, 0xffff0000, v154
	v_lshlrev_b32_e32 v172, 16, v155
	v_and_b32_e32 v173, 0xffff0000, v155
	v_pk_mul_f32 v[128:129], v[128:129], v[172:173]
	v_pk_mul_f32 v[126:127], v[126:127], v[170:171]
	global_store_dwordx4 v[156:157], v[126:129], off
	s_waitcnt vmcnt(3)
	v_lshlrev_b32_e32 v170, 16, v174
	v_and_b32_e32 v171, 0xffff0000, v174
	v_lshlrev_b32_e32 v172, 16, v175
	v_and_b32_e32 v173, 0xffff0000, v175
	v_pk_mul_f32 v[124:125], v[124:125], v[172:173]
	v_pk_mul_f32 v[122:123], v[122:123], v[170:171]
	global_store_dwordx4 v[156:157], v[122:125], off offset:64
	s_waitcnt vmcnt(3)
	v_lshlrev_b32_e32 v170, 16, v176
	v_and_b32_e32 v171, 0xffff0000, v176
	v_lshlrev_b32_e32 v172, 16, v177
	v_and_b32_e32 v173, 0xffff0000, v177
	v_pk_mul_f32 v[120:121], v[120:121], v[172:173]
	v_pk_mul_f32 v[118:119], v[118:119], v[170:171]
	global_store_dwordx4 v[156:157], v[118:121], off offset:512
	s_waitcnt vmcnt(3)
	v_lshlrev_b32_e32 v170, 16, v178
	v_and_b32_e32 v171, 0xffff0000, v178
	v_lshlrev_b32_e32 v172, 16, v179
	v_and_b32_e32 v173, 0xffff0000, v179
	v_pk_mul_f32 v[116:117], v[116:117], v[172:173]
	v_pk_mul_f32 v[114:115], v[114:115], v[170:171]
	global_store_dwordx4 v[156:157], v[114:117], off offset:576
.LBB0_1786:
	s_or_b64 exec, exec, s[22:23]
	s_nop 0
	v_add_u32_e32 v114, 16, v144
	v_cmp_gt_i32_e32 vcc, s54, v114
	s_and_saveexec_b64 s[22:23], vcc
	s_cbranch_execz .LBB0_1788
	v_ashrrev_i32_e32 v115, 31, v114
	v_lshlrev_b64 v[116:117], 11, v[114:115]
	v_lshl_add_u64 v[116:117], s[6:7], 0, v[116:117]
	v_lshl_add_u64 v[116:117], v[142:143], 1, v[116:117]
	global_load_dwordx2 v[118:119], v[116:117], off
	v_lshlrev_b64 v[114:115], 12, v[114:115]
	v_lshl_add_u64 v[114:115], s[8:9], 0, v[114:115]
	v_lshl_add_u64 v[114:115], v[142:143], 2, v[114:115]
	global_load_dwordx2 v[174:175], v[116:117], off offset:32
	global_load_dwordx2 v[176:177], v[116:117], off offset:256
	global_load_dwordx2 v[178:179], v[116:117], off offset:288
	s_waitcnt vmcnt(3)
	v_lshlrev_b32_e32 v170, 16, v118
	v_and_b32_e32 v171, 0xffff0000, v118
	v_lshlrev_b32_e32 v172, 16, v119
	v_and_b32_e32 v173, 0xffff0000, v119
	v_pk_mul_f32 v[112:113], v[112:113], v[172:173]
	v_pk_mul_f32 v[110:111], v[110:111], v[170:171]
	global_store_dwordx4 v[114:115], v[110:113], off
	s_waitcnt vmcnt(3)
	v_lshlrev_b32_e32 v170, 16, v174
	v_and_b32_e32 v171, 0xffff0000, v174
	v_lshlrev_b32_e32 v172, 16, v175
	v_and_b32_e32 v173, 0xffff0000, v175
	v_pk_mul_f32 v[108:109], v[108:109], v[172:173]
	v_pk_mul_f32 v[106:107], v[106:107], v[170:171]
	global_store_dwordx4 v[114:115], v[106:109], off offset:64
	s_waitcnt vmcnt(3)
	v_lshlrev_b32_e32 v170, 16, v176
	v_and_b32_e32 v171, 0xffff0000, v176
	v_lshlrev_b32_e32 v172, 16, v177
	v_and_b32_e32 v173, 0xffff0000, v177
	v_pk_mul_f32 v[104:105], v[104:105], v[172:173]
	v_pk_mul_f32 v[102:103], v[102:103], v[170:171]
	global_store_dwordx4 v[114:115], v[102:105], off offset:512
	s_waitcnt vmcnt(3)
	v_lshlrev_b32_e32 v170, 16, v178
	v_and_b32_e32 v171, 0xffff0000, v178
	v_lshlrev_b32_e32 v172, 16, v179
	v_and_b32_e32 v173, 0xffff0000, v179
	v_pk_mul_f32 v[100:101], v[100:101], v[172:173]
	v_pk_mul_f32 v[98:99], v[98:99], v[170:171]
	global_store_dwordx4 v[114:115], v[98:101], off offset:576
.LBB0_1788:
	s_or_b64 exec, exec, s[22:23]
	s_nop 0
	v_add_u32_e32 v98, 32, v144
	v_cmp_gt_i32_e32 vcc, s54, v98
	s_and_saveexec_b64 s[22:23], vcc
	s_cbranch_execz .LBB0_1790
	v_ashrrev_i32_e32 v99, 31, v98
	v_lshlrev_b64 v[100:101], 11, v[98:99]
	v_lshl_add_u64 v[100:101], s[6:7], 0, v[100:101]
	v_lshl_add_u64 v[100:101], v[142:143], 1, v[100:101]
	global_load_dwordx2 v[102:103], v[100:101], off
	v_lshlrev_b64 v[98:99], 12, v[98:99]
	v_lshl_add_u64 v[98:99], s[8:9], 0, v[98:99]
	v_lshl_add_u64 v[98:99], v[142:143], 2, v[98:99]
	global_load_dwordx2 v[174:175], v[100:101], off offset:32
	global_load_dwordx2 v[176:177], v[100:101], off offset:256
	global_load_dwordx2 v[178:179], v[100:101], off offset:288
	s_waitcnt vmcnt(3)
	v_lshlrev_b32_e32 v170, 16, v102
	v_and_b32_e32 v171, 0xffff0000, v102
	v_lshlrev_b32_e32 v172, 16, v103
	v_and_b32_e32 v173, 0xffff0000, v103
	v_pk_mul_f32 v[96:97], v[96:97], v[172:173]
	v_pk_mul_f32 v[94:95], v[94:95], v[170:171]
	global_store_dwordx4 v[98:99], v[94:97], off
	s_waitcnt vmcnt(3)
	v_lshlrev_b32_e32 v170, 16, v174
	v_and_b32_e32 v171, 0xffff0000, v174
	v_lshlrev_b32_e32 v172, 16, v175
	v_and_b32_e32 v173, 0xffff0000, v175
	v_pk_mul_f32 v[92:93], v[92:93], v[172:173]
	v_pk_mul_f32 v[90:91], v[90:91], v[170:171]
	global_store_dwordx4 v[98:99], v[90:93], off offset:64
	s_waitcnt vmcnt(3)
	v_lshlrev_b32_e32 v170, 16, v176
	v_and_b32_e32 v171, 0xffff0000, v176
	v_lshlrev_b32_e32 v172, 16, v177
	v_and_b32_e32 v173, 0xffff0000, v177
	v_pk_mul_f32 v[88:89], v[88:89], v[172:173]
	v_pk_mul_f32 v[86:87], v[86:87], v[170:171]
	global_store_dwordx4 v[98:99], v[86:89], off offset:512
	s_waitcnt vmcnt(3)
	v_lshlrev_b32_e32 v170, 16, v178
	v_and_b32_e32 v171, 0xffff0000, v178
	v_lshlrev_b32_e32 v172, 16, v179
	v_and_b32_e32 v173, 0xffff0000, v179
	v_pk_mul_f32 v[84:85], v[84:85], v[172:173]
	v_pk_mul_f32 v[82:83], v[82:83], v[170:171]
	global_store_dwordx4 v[98:99], v[82:85], off offset:576
; __device__ __forceinline__ unsigned cvt_pk_bf16(float lo, float hi) { typedef float f2_ __attribute__((ext_vector_type(2))); typedef __bf16 b2_ __attribute__((ext_vector_type(2))); f2_ v = {lo, hi}; b2_ b = __builtin_convertvector(v, b2_); return __builtin_bit_cast(unsigned, b); }
;     DEV void apply(int r, int c, const f32x4 v) const { st_bf16x4(MG + (size_t)r * DM + c, *(const f32x4*)(PT + (size_t)r * DM + c) + v * ld_bf16x4(SG + (size_t)r * DM + c)); }
; DEV f32x4 ld_bf16x4(const bf16* p) { const v2u w = *(const v2u*)p; return (f32x4){bflo(w.x), bfhi(w.x), bflo(w.y), bfhi(w.y)}; }
; DEV void st_bf16x4(bf16* p, const f32x4 v) { v2u w; w.x = pg8::cvt_pk_bf16(v[0], v[1]); w.y = pg8::cvt_pk_bf16(v[2], v[3]); *(v2u*)p = w; }
;     DEV void apply(int r, int c, const f32x4 v) const { *(f32x4*)(PT + (size_t)r * DM + c) = v * ld_bf16x4(SG + (size_t)r * DM + c); }
;     DEV void operator()(const f32x4 (&acc)[2][2][4][2], const pg8::Unit& u, int wr, int wc, int fr_, int fq_) const { int fr = fr_, fq = fq_; asm volatile("" : "+v"(fr), "+v"(fq));
;         EPI_ALL({ apply(r, c, v); }) }
.LBB0_1790:
	s_or_b64 exec, exec, s[22:23]
	s_nop 0
	v_add_u32_e32 v82, 48, v144
	v_cmp_gt_i32_e32 vcc, s54, v82
	s_and_saveexec_b64 s[22:23], vcc
	s_cbranch_execz .LBB0_1792
	v_ashrrev_i32_e32 v83, 31, v82
	v_lshlrev_b64 v[84:85], 11, v[82:83]
	v_lshl_add_u64 v[84:85], s[6:7], 0, v[84:85]
	v_lshl_add_u64 v[84:85], v[142:143], 1, v[84:85]
	global_load_dwordx2 v[86:87], v[84:85], off
	v_lshlrev_b64 v[82:83], 12, v[82:83]
	v_lshl_add_u64 v[82:83], s[8:9], 0, v[82:83]
	v_lshl_add_u64 v[82:83], v[142:143], 2, v[82:83]
	global_load_dwordx2 v[174:175], v[84:85], off offset:32
	global_load_dwordx2 v[176:177], v[84:85], off offset:256
	global_load_dwordx2 v[178:179], v[84:85], off offset:288
	s_waitcnt vmcnt(3)
	v_lshlrev_b32_e32 v170, 16, v86
	v_and_b32_e32 v171, 0xffff0000, v86
	v_lshlrev_b32_e32 v172, 16, v87
	v_and_b32_e32 v173, 0xffff0000, v87
	v_pk_mul_f32 v[80:81], v[80:81], v[172:173]
	v_pk_mul_f32 v[78:79], v[78:79], v[170:171]
	global_store_dwordx4 v[82:83], v[78:81], off
	s_waitcnt vmcnt(3)
	v_lshlrev_b32_e32 v170, 16, v174
	v_and_b32_e32 v171, 0xffff0000, v174
	v_lshlrev_b32_e32 v172, 16, v175
	v_and_b32_e32 v173, 0xffff0000, v175
	v_pk_mul_f32 v[76:77], v[76:77], v[172:173]
	v_pk_mul_f32 v[74:75], v[74:75], v[170:171]
	global_store_dwordx4 v[82:83], v[74:77], off offset:64
	s_waitcnt vmcnt(3)
	v_lshlrev_b32_e32 v170, 16, v176
	v_and_b32_e32 v171, 0xffff0000, v176
	v_lshlrev_b32_e32 v172, 16, v177
	v_and_b32_e32 v173, 0xffff0000, v177
	v_pk_mul_f32 v[72:73], v[72:73], v[172:173]
	v_pk_mul_f32 v[70:71], v[70:71], v[170:171]
	global_store_dwordx4 v[82:83], v[70:73], off offset:512
	s_waitcnt vmcnt(3)
	v_lshlrev_b32_e32 v170, 16, v178
	v_and_b32_e32 v171, 0xffff0000, v178
	v_lshlrev_b32_e32 v172, 16, v179
	v_and_b32_e32 v173, 0xffff0000, v179
	v_pk_mul_f32 v[68:69], v[68:69], v[172:173]
	v_pk_mul_f32 v[66:67], v[66:67], v[170:171]
	global_store_dwordx4 v[82:83], v[66:69], off offset:576
.LBB0_1792:
	s_or_b64 exec, exec, s[22:23]
	s_nop 0
	v_add_u32_e32 v66, 0x80, v144
	v_cmp_gt_i32_e32 vcc, s54, v66
	s_and_saveexec_b64 s[22:23], vcc
	s_cbranch_execz .LBB0_1794
	v_ashrrev_i32_e32 v67, 31, v66
	v_lshlrev_b64 v[68:69], 11, v[66:67]
	v_lshl_add_u64 v[68:69], s[6:7], 0, v[68:69]
	v_lshl_add_u64 v[68:69], v[142:143], 1, v[68:69]
	global_load_dwordx2 v[70:71], v[68:69], off
	v_lshlrev_b64 v[66:67], 12, v[66:67]
	v_lshl_add_u64 v[66:67], s[8:9], 0, v[66:67]
	v_lshl_add_u64 v[66:67], v[142:143], 2, v[66:67]
	global_load_dwordx2 v[174:175], v[68:69], off offset:32
	global_load_dwordx2 v[176:177], v[68:69], off offset:256
	global_load_dwordx2 v[178:179], v[68:69], off offset:288
	s_waitcnt vmcnt(3)
	v_lshlrev_b32_e32 v170, 16, v70
	v_and_b32_e32 v171, 0xffff0000, v70
	v_lshlrev_b32_e32 v172, 16, v71
	v_and_b32_e32 v173, 0xffff0000, v71
	v_pk_mul_f32 v[64:65], v[64:65], v[172:173]
	v_pk_mul_f32 v[62:63], v[62:63], v[170:171]
	global_store_dwordx4 v[66:67], v[62:65], off
	s_waitcnt vmcnt(3)
	v_lshlrev_b32_e32 v170, 16, v174
	v_and_b32_e32 v171, 0xffff0000, v174
	v_lshlrev_b32_e32 v172, 16, v175
	v_and_b32_e32 v173, 0xffff0000, v175
	v_pk_mul_f32 v[60:61], v[60:61], v[172:173]
	v_pk_mul_f32 v[58:59], v[58:59], v[170:171]
	global_store_dwordx4 v[66:67], v[58:61], off offset:64
	s_waitcnt vmcnt(3)
	v_lshlrev_b32_e32 v170, 16, v176
	v_and_b32_e32 v171, 0xffff0000, v176
	v_lshlrev_b32_e32 v172, 16, v177
	v_and_b32_e32 v173, 0xffff0000, v177
	v_pk_mul_f32 v[56:57], v[56:57], v[172:173]
	v_pk_mul_f32 v[54:55], v[54:55], v[170:171]
	global_store_dwordx4 v[66:67], v[54:57], off offset:512
	s_waitcnt vmcnt(3)
	v_lshlrev_b32_e32 v170, 16, v178
	v_and_b32_e32 v171, 0xffff0000, v178
	v_lshlrev_b32_e32 v172, 16, v179
	v_and_b32_e32 v173, 0xffff0000, v179
	v_pk_mul_f32 v[52:53], v[52:53], v[172:173]
	v_pk_mul_f32 v[50:51], v[50:51], v[170:171]
	global_store_dwordx4 v[66:67], v[50:53], off offset:576
; __device__ __forceinline__ unsigned cvt_pk_bf16(float lo, float hi) { typedef float f2_ __attribute__((ext_vector_type(2))); typedef __bf16 b2_ __attribute__((ext_vector_type(2))); f2_ v = {lo, hi}; b2_ b = __builtin_convertvector(v, b2_); return __builtin_bit_cast(unsigned, b); }
;     DEV void apply(int r, int c, const f32x4 v) const { st_bf16x4(MG + (size_t)r * DM + c, *(const f32x4*)(PT + (size_t)r * DM + c) + v * ld_bf16x4(SG + (size_t)r * DM + c)); }
; DEV f32x4 ld_bf16x4(const bf16* p) { const v2u w = *(const v2u*)p; return (f32x4){bflo(w.x), bfhi(w.x), bflo(w.y), bfhi(w.y)}; }
; DEV void st_bf16x4(bf16* p, const f32x4 v) { v2u w; w.x = pg8::cvt_pk_bf16(v[0], v[1]); w.y = pg8::cvt_pk_bf16(v[2], v[3]); *(v2u*)p = w; }
;     DEV void apply(int r, int c, const f32x4 v) const { *(f32x4*)(PT + (size_t)r * DM + c) = v * ld_bf16x4(SG + (size_t)r * DM + c); }
;     DEV void operator()(const f32x4 (&acc)[2][2][4][2], const pg8::Unit& u, int wr, int wc, int fr_, int fq_) const { int fr = fr_, fq = fq_; asm volatile("" : "+v"(fr), "+v"(fq));
;         EPI_ALL({ apply(r, c, v); }) }
.LBB0_1794:
	s_or_b64 exec, exec, s[22:23]
	s_nop 0
	v_add_u32_e32 v50, 0x90, v144
	v_cmp_gt_i32_e32 vcc, s54, v50
	s_and_saveexec_b64 s[22:23], vcc
	s_cbranch_execz .LBB0_1796
	v_ashrrev_i32_e32 v51, 31, v50
	v_lshlrev_b64 v[52:53], 11, v[50:51]
	v_lshl_add_u64 v[52:53], s[6:7], 0, v[52:53]
	v_lshl_add_u64 v[52:53], v[142:143], 1, v[52:53]
	global_load_dwordx2 v[54:55], v[52:53], off
	v_lshlrev_b64 v[50:51], 12, v[50:51]
	v_lshl_add_u64 v[50:51], s[8:9], 0, v[50:51]
	v_lshl_add_u64 v[50:51], v[142:143], 2, v[50:51]
	global_load_dwordx2 v[174:175], v[52:53], off offset:32
	global_load_dwordx2 v[176:177], v[52:53], off offset:256
	global_load_dwordx2 v[178:179], v[52:53], off offset:288
	s_waitcnt vmcnt(3)
	v_lshlrev_b32_e32 v170, 16, v54
	v_and_b32_e32 v171, 0xffff0000, v54
	v_lshlrev_b32_e32 v172, 16, v55
	v_and_b32_e32 v173, 0xffff0000, v55
	v_pk_mul_f32 v[48:49], v[48:49], v[172:173]
	v_pk_mul_f32 v[46:47], v[46:47], v[170:171]
	global_store_dwordx4 v[50:51], v[46:49], off
	s_waitcnt vmcnt(3)
	v_lshlrev_b32_e32 v170, 16, v174
	v_and_b32_e32 v171, 0xffff0000, v174
	v_lshlrev_b32_e32 v172, 16, v175
	v_and_b32_e32 v173, 0xffff0000, v175
	v_pk_mul_f32 v[44:45], v[44:45], v[172:173]
	v_pk_mul_f32 v[42:43], v[42:43], v[170:171]
	global_store_dwordx4 v[50:51], v[42:45], off offset:64
	s_waitcnt vmcnt(3)
	v_lshlrev_b32_e32 v170, 16, v176
	v_and_b32_e32 v171, 0xffff0000, v176
	v_lshlrev_b32_e32 v172, 16, v177
	v_and_b32_e32 v173, 0xffff0000, v177
	v_pk_mul_f32 v[40:41], v[40:41], v[172:173]
	v_pk_mul_f32 v[38:39], v[38:39], v[170:171]
	global_store_dwordx4 v[50:51], v[38:41], off offset:512
	s_waitcnt vmcnt(3)
	v_lshlrev_b32_e32 v170, 16, v178
	v_and_b32_e32 v171, 0xffff0000, v178
	v_lshlrev_b32_e32 v172, 16, v179
	v_and_b32_e32 v173, 0xffff0000, v179
	v_pk_mul_f32 v[36:37], v[36:37], v[172:173]
	v_pk_mul_f32 v[34:35], v[34:35], v[170:171]
	global_store_dwordx4 v[50:51], v[34:37], off offset:576
.LBB0_1796:
	s_or_b64 exec, exec, s[22:23]
	s_nop 0
	v_add_u32_e32 v34, 0xa0, v144
	v_cmp_gt_i32_e32 vcc, s54, v34
	s_and_saveexec_b64 s[22:23], vcc
	s_cbranch_execz .LBB0_1798
	v_ashrrev_i32_e32 v35, 31, v34
	v_lshlrev_b64 v[36:37], 11, v[34:35]
	v_lshl_add_u64 v[36:37], s[6:7], 0, v[36:37]
	v_lshl_add_u64 v[36:37], v[142:143], 1, v[36:37]
	global_load_dwordx2 v[38:39], v[36:37], off
	v_lshlrev_b64 v[34:35], 12, v[34:35]
	v_lshl_add_u64 v[34:35], s[8:9], 0, v[34:35]
	v_lshl_add_u64 v[34:35], v[142:143], 2, v[34:35]
	global_load_dwordx2 v[174:175], v[36:37], off offset:32
	global_load_dwordx2 v[176:177], v[36:37], off offset:256
	global_load_dwordx2 v[178:179], v[36:37], off offset:288
	s_waitcnt vmcnt(3)
	v_lshlrev_b32_e32 v170, 16, v38
	v_and_b32_e32 v171, 0xffff0000, v38
	v_lshlrev_b32_e32 v172, 16, v39
	v_and_b32_e32 v173, 0xffff0000, v39
	v_pk_mul_f32 v[32:33], v[32:33], v[172:173]
	v_pk_mul_f32 v[30:31], v[30:31], v[170:171]
	global_store_dwordx4 v[34:35], v[30:33], off
	s_waitcnt vmcnt(3)
	v_lshlrev_b32_e32 v170, 16, v174
	v_and_b32_e32 v171, 0xffff0000, v174
	v_lshlrev_b32_e32 v172, 16, v175
	v_and_b32_e32 v173, 0xffff0000, v175
	v_pk_mul_f32 v[28:29], v[28:29], v[172:173]
	v_pk_mul_f32 v[26:27], v[26:27], v[170:171]
	global_store_dwordx4 v[34:35], v[26:29], off offset:64
	s_waitcnt vmcnt(3)
	v_lshlrev_b32_e32 v170, 16, v176
	v_and_b32_e32 v171, 0xffff0000, v176
	v_lshlrev_b32_e32 v172, 16, v177
	v_and_b32_e32 v173, 0xffff0000, v177
	v_pk_mul_f32 v[24:25], v[24:25], v[172:173]
	v_pk_mul_f32 v[22:23], v[22:23], v[170:171]
	global_store_dwordx4 v[34:35], v[22:25], off offset:512
	s_waitcnt vmcnt(3)
	v_lshlrev_b32_e32 v170, 16, v178
	v_and_b32_e32 v171, 0xffff0000, v178
	v_lshlrev_b32_e32 v172, 16, v179
	v_and_b32_e32 v173, 0xffff0000, v179
	v_pk_mul_f32 v[20:21], v[20:21], v[172:173]
	v_pk_mul_f32 v[18:19], v[18:19], v[170:171]
	global_store_dwordx4 v[34:35], v[18:21], off offset:576
.LBB0_1798:
	s_or_b64 exec, exec, s[22:23]
	s_nop 0
	v_add_u32_e32 v18, 0xb0, v144
	v_cmp_gt_i32_e32 vcc, s54, v18
	s_and_saveexec_b64 s[22:23], vcc
	s_cbranch_execz .LBB0_1800
	v_ashrrev_i32_e32 v19, 31, v18
	v_lshlrev_b64 v[20:21], 11, v[18:19]
	v_lshl_add_u64 v[20:21], s[6:7], 0, v[20:21]
	v_lshl_add_u64 v[20:21], v[142:143], 1, v[20:21]
	global_load_dwordx2 v[22:23], v[20:21], off
	v_lshlrev_b64 v[18:19], 12, v[18:19]
	v_lshl_add_u64 v[18:19], s[8:9], 0, v[18:19]
	v_lshl_add_u64 v[18:19], v[142:143], 2, v[18:19]
	global_load_dwordx2 v[174:175], v[20:21], off offset:32
	global_load_dwordx2 v[176:177], v[20:21], off offset:256
	global_load_dwordx2 v[178:179], v[20:21], off offset:288
	s_waitcnt vmcnt(3)
	v_lshlrev_b32_e32 v170, 16, v22
	v_and_b32_e32 v171, 0xffff0000, v22
	v_lshlrev_b32_e32 v172, 16, v23
	v_and_b32_e32 v173, 0xffff0000, v23
	v_pk_mul_f32 v[16:17], v[16:17], v[172:173]
	v_pk_mul_f32 v[14:15], v[14:15], v[170:171]
	global_store_dwordx4 v[18:19], v[14:17], off
	s_waitcnt vmcnt(3)
	v_lshlrev_b32_e32 v170, 16, v174
	v_and_b32_e32 v171, 0xffff0000, v174
	v_lshlrev_b32_e32 v172, 16, v175
	v_and_b32_e32 v173, 0xffff0000, v175
	v_pk_mul_f32 v[12:13], v[12:13], v[172:173]
	v_pk_mul_f32 v[10:11], v[10:11], v[170:171]
	global_store_dwordx4 v[18:19], v[10:13], off offset:64
	s_waitcnt vmcnt(3)
	v_lshlrev_b32_e32 v170, 16, v176
	v_and_b32_e32 v171, 0xffff0000, v176
	v_lshlrev_b32_e32 v172, 16, v177
	v_and_b32_e32 v173, 0xffff0000, v177
	v_pk_mul_f32 v[8:9], v[8:9], v[172:173]
	v_pk_mul_f32 v[6:7], v[6:7], v[170:171]
	global_store_dwordx4 v[18:19], v[6:9], off offset:512
	s_waitcnt vmcnt(3)
	v_lshlrev_b32_e32 v170, 16, v178
	v_and_b32_e32 v171, 0xffff0000, v178
	v_lshlrev_b32_e32 v172, 16, v179
	v_and_b32_e32 v173, 0xffff0000, v179
	v_pk_mul_f32 v[4:5], v[4:5], v[172:173]
	v_pk_mul_f32 v[2:3], v[2:3], v[170:171]
	global_store_dwordx4 v[18:19], v[2:5], off offset:576

; __device__ __forceinline__ unsigned cvt_pk_bf16(float lo, float hi) { typedef float f2_ __attribute__((ext_vector_type(2))); typedef __bf16 b2_ __attribute__((ext_vector_type(2))); f2_ v = {lo, hi}; b2_ b = __builtin_convertvector(v, b2_); return __builtin_bit_cast(unsigned, b); }
;     DEV void apply(int r, int c, const f32x4 v) const { *(f32x4*)(PT + (size_t)r * DM + c) = v * ld_bf16x4(SG + (size_t)r * DM + c); }
; DEV f32x4 ld_bf16x4(const bf16* p) { const v2u w = *(const v2u*)p; return (f32x4){bflo(w.x), bfhi(w.x), bflo(w.y), bfhi(w.y)}; }
; DEV void st_bf16x4(bf16* p, const f32x4 v) { v2u w; w.x = pg8::cvt_pk_bf16(v[0], v[1]); w.y = pg8::cvt_pk_bf16(v[2], v[3]); *(v2u*)p = w; }
;     DEV void apply(int r, int c, const f32x4 v) const { st_bf16x4(MG + (size_t)r * DM + c, *(const f32x4*)(PT + (size_t)r * DM + c) + v * ld_bf16x4(SG + (size_t)r * DM + c)); }
;     DEV void operator()(const f32x4 (&acc)[2][2][4][2], const pg8::Unit& u, int wr, int wc, int fr_, int fq_) const { int fr = fr_, fq = fq_; asm volatile("" : "+v"(fr), "+v"(fq));
;         EPI_ALL({ apply(r, c, v); }) }
.LBB0_1836:
	s_lshl_b32 s19, s24, 8
	v_mov_b32_e32 v142, v1
	v_mov_b32_e32 v143, v146
	s_add_i32 s19, s19, s48
	s_nop 0
	v_add_u32_e32 v144, s19, v142
	s_lshl_b32 s19, s26, 8
	s_or_b32 s19, s19, s49
	v_lshl_add_u32 v142, v143, 2, s19
	v_cmp_gt_i32_e32 vcc, s56, v144
	v_ashrrev_i32_e32 v143, 31, v142
	s_and_saveexec_b64 s[24:25], vcc
	s_cbranch_execz .LBB0_1838
	v_ashrrev_i32_e32 v145, 31, v144
	v_lshlrev_b64 v[156:157], 11, v[144:145]
	v_lshlrev_b64 v[158:159], 1, v[142:143]
	v_lshl_add_u64 v[152:153], s[6:7], 0, v[156:157]
	v_lshl_add_u64 v[160:161], v[152:153], 0, v[158:159]
	v_lshlrev_b64 v[152:153], 12, v[144:145]
	v_lshl_add_u64 v[152:153], s[8:9], 0, v[152:153]
	global_load_dwordx2 v[162:163], v[160:161], off
	v_lshl_add_u64 v[164:165], v[142:143], 2, v[152:153]
	global_load_dwordx4 v[152:155], v[164:165], off
	v_lshl_add_u64 v[156:157], s[10:11], 0, v[156:157]
	v_lshl_add_u64 v[156:157], v[156:157], 0, v[158:159]
	global_load_dwordx2 v[174:175], v[160:161], off offset:32
	global_load_dwordx4 v[176:179], v[164:165], off offset:64
	global_load_dwordx2 v[180:181], v[160:161], off offset:256
	global_load_dwordx4 v[182:185], v[164:165], off offset:512
	global_load_dwordx2 v[186:187], v[160:161], off offset:288
	global_load_dwordx4 v[188:191], v[164:165], off offset:576
	s_waitcnt vmcnt(6)
	v_lshlrev_b32_e32 v170, 16, v162
	v_and_b32_e32 v171, 0xffff0000, v162
	v_lshlrev_b32_e32 v172, 16, v163
	v_and_b32_e32 v173, 0xffff0000, v163
	v_pk_fma_f32 v[128:129], v[128:129], v[172:173], v[154:155]
	v_pk_fma_f32 v[126:127], v[126:127], v[170:171], v[152:153]
	v_cvt_pk_bf16_f32 v126, v126, v127
	v_cvt_pk_bf16_f32 v127, v128, v129
	global_store_dwordx2 v[156:157], v[126:127], off
	s_waitcnt vmcnt(5)
	v_lshlrev_b32_e32 v170, 16, v174
	v_and_b32_e32 v171, 0xffff0000, v174
	v_lshlrev_b32_e32 v172, 16, v175
	v_and_b32_e32 v173, 0xffff0000, v175
	v_pk_fma_f32 v[124:125], v[124:125], v[172:173], v[178:179]
	v_pk_fma_f32 v[122:123], v[122:123], v[170:171], v[176:177]
	v_cvt_pk_bf16_f32 v122, v122, v123
	v_cvt_pk_bf16_f32 v123, v124, v125
	global_store_dwordx2 v[156:157], v[122:123], off offset:32
	s_waitcnt vmcnt(4)
	v_lshlrev_b32_e32 v170, 16, v180
	v_and_b32_e32 v171, 0xffff0000, v180
	v_lshlrev_b32_e32 v172, 16, v181
	v_and_b32_e32 v173, 0xffff0000, v181
	v_pk_fma_f32 v[120:121], v[120:121], v[172:173], v[184:185]
	v_pk_fma_f32 v[118:119], v[118:119], v[170:171], v[182:183]
	v_cvt_pk_bf16_f32 v118, v118, v119
	v_cvt_pk_bf16_f32 v119, v120, v121
	global_store_dwordx2 v[156:157], v[118:119], off offset:256
	s_waitcnt vmcnt(3)
	v_lshlrev_b32_e32 v170, 16, v186
	v_and_b32_e32 v171, 0xffff0000, v186
	v_lshlrev_b32_e32 v172, 16, v187
	v_and_b32_e32 v173, 0xffff0000, v187
	v_pk_fma_f32 v[116:117], v[116:117], v[172:173], v[190:191]
	v_pk_fma_f32 v[114:115], v[114:115], v[170:171], v[188:189]
	v_cvt_pk_bf16_f32 v114, v114, v115
	v_cvt_pk_bf16_f32 v115, v116, v117
	global_store_dwordx2 v[156:157], v[114:115], off offset:288
.LBB0_1838:
	s_or_b64 exec, exec, s[24:25]
	v_add_u32_e32 v114, 16, v144
	v_cmp_gt_i32_e32 vcc, s56, v114
	s_and_saveexec_b64 s[24:25], vcc
	s_cbranch_execz .LBB0_1840
	v_ashrrev_i32_e32 v115, 31, v114
	v_lshlrev_b64 v[118:119], 11, v[114:115]
	v_lshlrev_b64 v[120:121], 1, v[142:143]
	v_lshl_add_u64 v[116:117], s[6:7], 0, v[118:119]
	v_lshlrev_b64 v[114:115], 12, v[114:115]
	v_lshl_add_u64 v[122:123], v[116:117], 0, v[120:121]
	v_lshl_add_u64 v[114:115], s[8:9], 0, v[114:115]
	global_load_dwordx2 v[124:125], v[122:123], off
	v_lshl_add_u64 v[126:127], v[142:143], 2, v[114:115]
	global_load_dwordx4 v[114:117], v[126:127], off
	v_lshl_add_u64 v[118:119], s[10:11], 0, v[118:119]
	v_lshl_add_u64 v[118:119], v[118:119], 0, v[120:121]
	global_load_dwordx2 v[174:175], v[122:123], off offset:32
	global_load_dwordx4 v[176:179], v[126:127], off offset:64
	global_load_dwordx2 v[180:181], v[122:123], off offset:256
	global_load_dwordx4 v[182:185], v[126:127], off offset:512
	global_load_dwordx2 v[186:187], v[122:123], off offset:288
	global_load_dwordx4 v[188:191], v[126:127], off offset:576
	s_waitcnt vmcnt(6)
	v_lshlrev_b32_e32 v170, 16, v124
	v_and_b32_e32 v171, 0xffff0000, v124
	v_lshlrev_b32_e32 v172, 16, v125
	v_and_b32_e32 v173, 0xffff0000, v125
	v_pk_fma_f32 v[112:113], v[112:113], v[172:173], v[116:117]
	v_pk_fma_f32 v[110:111], v[110:111], v[170:171], v[114:115]
	v_cvt_pk_bf16_f32 v110, v110, v111
	v_cvt_pk_bf16_f32 v111, v112, v113
	global_store_dwordx2 v[118:119], v[110:111], off
	s_waitcnt vmcnt(5)
	v_lshlrev_b32_e32 v170, 16, v174
	v_and_b32_e32 v171, 0xffff0000, v174
	v_lshlrev_b32_e32 v172, 16, v175
	v_and_b32_e32 v173, 0xffff0000, v175
	v_pk_fma_f32 v[108:109], v[108:109], v[172:173], v[178:179]
	v_pk_fma_f32 v[106:107], v[106:107], v[170:171], v[176:177]
	v_cvt_pk_bf16_f32 v106, v106, v107
	v_cvt_pk_bf16_f32 v107, v108, v109
	global_store_dwordx2 v[118:119], v[106:107], off offset:32
	s_waitcnt vmcnt(4)
	v_lshlrev_b32_e32 v170, 16, v180
	v_and_b32_e32 v171, 0xffff0000, v180
	v_lshlrev_b32_e32 v172, 16, v181
	v_and_b32_e32 v173, 0xffff0000, v181
	v_pk_fma_f32 v[104:105], v[104:105], v[172:173], v[184:185]
	v_pk_fma_f32 v[102:103], v[102:103], v[170:171], v[182:183]
	v_cvt_pk_bf16_f32 v102, v102, v103
	v_cvt_pk_bf16_f32 v103, v104, v105
	global_store_dwordx2 v[118:119], v[102:103], off offset:256
	s_waitcnt vmcnt(3)
	v_lshlrev_b32_e32 v170, 16, v186
	v_and_b32_e32 v171, 0xffff0000, v186
	v_lshlrev_b32_e32 v172, 16, v187
	v_and_b32_e32 v173, 0xffff0000, v187
	v_pk_fma_f32 v[100:101], v[100:101], v[172:173], v[190:191]
	v_pk_fma_f32 v[98:99], v[98:99], v[170:171], v[188:189]
	v_cvt_pk_bf16_f32 v98, v98, v99
	v_cvt_pk_bf16_f32 v99, v100, v101
	global_store_dwordx2 v[118:119], v[98:99], off offset:288
; __device__ __forceinline__ unsigned cvt_pk_bf16(float lo, float hi) { typedef float f2_ __attribute__((ext_vector_type(2))); typedef __bf16 b2_ __attribute__((ext_vector_type(2))); f2_ v = {lo, hi}; b2_ b = __builtin_convertvector(v, b2_); return __builtin_bit_cast(unsigned, b); }
;     DEV void apply(int r, int c, const f32x4 v) const { *(f32x4*)(PT + (size_t)r * DM + c) = v * ld_bf16x4(SG + (size_t)r * DM + c); }
; DEV f32x4 ld_bf16x4(const bf16* p) { const v2u w = *(const v2u*)p; return (f32x4){bflo(w.x), bfhi(w.x), bflo(w.y), bfhi(w.y)}; }
; DEV void st_bf16x4(bf16* p, const f32x4 v) { v2u w; w.x = pg8::cvt_pk_bf16(v[0], v[1]); w.y = pg8::cvt_pk_bf16(v[2], v[3]); *(v2u*)p = w; }
;     DEV void apply(int r, int c, const f32x4 v) const { st_bf16x4(MG + (size_t)r * DM + c, *(const f32x4*)(PT + (size_t)r * DM + c) + v * ld_bf16x4(SG + (size_t)r * DM + c)); }
;     DEV void operator()(const f32x4 (&acc)[2][2][4][2], const pg8::Unit& u, int wr, int wc, int fr_, int fq_) const { int fr = fr_, fq = fq_; asm volatile("" : "+v"(fr), "+v"(fq));
;         EPI_ALL({ apply(r, c, v); }) }
.LBB0_1840:
	s_or_b64 exec, exec, s[24:25]
	v_add_u32_e32 v98, 32, v144
	v_cmp_gt_i32_e32 vcc, s56, v98
	s_and_saveexec_b64 s[24:25], vcc
	s_cbranch_execz .LBB0_1842
	v_ashrrev_i32_e32 v99, 31, v98
	v_lshlrev_b64 v[102:103], 11, v[98:99]
	v_lshlrev_b64 v[104:105], 1, v[142:143]
	v_lshl_add_u64 v[100:101], s[6:7], 0, v[102:103]
	v_lshlrev_b64 v[98:99], 12, v[98:99]
	v_lshl_add_u64 v[106:107], v[100:101], 0, v[104:105]
	v_lshl_add_u64 v[98:99], s[8:9], 0, v[98:99]
	global_load_dwordx2 v[108:109], v[106:107], off
	v_lshl_add_u64 v[110:111], v[142:143], 2, v[98:99]
	global_load_dwordx4 v[98:101], v[110:111], off
	v_lshl_add_u64 v[102:103], s[10:11], 0, v[102:103]
	v_lshl_add_u64 v[102:103], v[102:103], 0, v[104:105]
	global_load_dwordx2 v[174:175], v[106:107], off offset:32
	global_load_dwordx4 v[176:179], v[110:111], off offset:64
	global_load_dwordx2 v[180:181], v[106:107], off offset:256
	global_load_dwordx4 v[182:185], v[110:111], off offset:512
	global_load_dwordx2 v[186:187], v[106:107], off offset:288
	global_load_dwordx4 v[188:191], v[110:111], off offset:576
	s_waitcnt vmcnt(6)
	v_lshlrev_b32_e32 v170, 16, v108
	v_and_b32_e32 v171, 0xffff0000, v108
	v_lshlrev_b32_e32 v172, 16, v109
	v_and_b32_e32 v173, 0xffff0000, v109
	v_pk_fma_f32 v[96:97], v[96:97], v[172:173], v[100:101]
	v_pk_fma_f32 v[94:95], v[94:95], v[170:171], v[98:99]
	v_cvt_pk_bf16_f32 v94, v94, v95
	v_cvt_pk_bf16_f32 v95, v96, v97
	global_store_dwordx2 v[102:103], v[94:95], off
	s_waitcnt vmcnt(5)
	v_lshlrev_b32_e32 v170, 16, v174
	v_and_b32_e32 v171, 0xffff0000, v174
	v_lshlrev_b32_e32 v172, 16, v175
	v_and_b32_e32 v173, 0xffff0000, v175
	v_pk_fma_f32 v[92:93], v[92:93], v[172:173], v[178:179]
	v_pk_fma_f32 v[90:91], v[90:91], v[170:171], v[176:177]
	v_cvt_pk_bf16_f32 v90, v90, v91
	v_cvt_pk_bf16_f32 v91, v92, v93
	global_store_dwordx2 v[102:103], v[90:91], off offset:32
	s_waitcnt vmcnt(4)
	v_lshlrev_b32_e32 v170, 16, v180
	v_and_b32_e32 v171, 0xffff0000, v180
	v_lshlrev_b32_e32 v172, 16, v181
	v_and_b32_e32 v173, 0xffff0000, v181
	v_pk_fma_f32 v[88:89], v[88:89], v[172:173], v[184:185]
	v_pk_fma_f32 v[86:87], v[86:87], v[170:171], v[182:183]
	v_cvt_pk_bf16_f32 v86, v86, v87
	v_cvt_pk_bf16_f32 v87, v88, v89
	global_store_dwordx2 v[102:103], v[86:87], off offset:256
	s_waitcnt vmcnt(3)
	v_lshlrev_b32_e32 v170, 16, v186
	v_and_b32_e32 v171, 0xffff0000, v186
	v_lshlrev_b32_e32 v172, 16, v187
	v_and_b32_e32 v173, 0xffff0000, v187
	v_pk_fma_f32 v[84:85], v[84:85], v[172:173], v[190:191]
	v_pk_fma_f32 v[82:83], v[82:83], v[170:171], v[188:189]
	v_cvt_pk_bf16_f32 v82, v82, v83
	v_cvt_pk_bf16_f32 v83, v84, v85
	global_store_dwordx2 v[102:103], v[82:83], off offset:288
.LBB0_1842:
	s_or_b64 exec, exec, s[24:25]
	v_add_u32_e32 v82, 48, v144
	v_cmp_gt_i32_e32 vcc, s56, v82
	s_and_saveexec_b64 s[24:25], vcc
	s_cbranch_execz .LBB0_1844
	v_ashrrev_i32_e32 v83, 31, v82
	v_lshlrev_b64 v[86:87], 11, v[82:83]
	v_lshlrev_b64 v[88:89], 1, v[142:143]
	v_lshl_add_u64 v[84:85], s[6:7], 0, v[86:87]
	v_lshlrev_b64 v[82:83], 12, v[82:83]
	v_lshl_add_u64 v[90:91], v[84:85], 0, v[88:89]
	v_lshl_add_u64 v[82:83], s[8:9], 0, v[82:83]
	global_load_dwordx2 v[92:93], v[90:91], off
	v_lshl_add_u64 v[94:95], v[142:143], 2, v[82:83]
	global_load_dwordx4 v[82:85], v[94:95], off
	v_lshl_add_u64 v[86:87], s[10:11], 0, v[86:87]
	v_lshl_add_u64 v[86:87], v[86:87], 0, v[88:89]
	global_load_dwordx2 v[174:175], v[90:91], off offset:32
	global_load_dwordx4 v[176:179], v[94:95], off offset:64
	global_load_dwordx2 v[180:181], v[90:91], off offset:256
	global_load_dwordx4 v[182:185], v[94:95], off offset:512
	global_load_dwordx2 v[186:187], v[90:91], off offset:288
	global_load_dwordx4 v[188:191], v[94:95], off offset:576
	s_waitcnt vmcnt(6)
	v_lshlrev_b32_e32 v170, 16, v92
	v_and_b32_e32 v171, 0xffff0000, v92
	v_lshlrev_b32_e32 v172, 16, v93
	v_and_b32_e32 v173, 0xffff0000, v93
	v_pk_fma_f32 v[80:81], v[80:81], v[172:173], v[84:85]
	v_pk_fma_f32 v[78:79], v[78:79], v[170:171], v[82:83]
	v_cvt_pk_bf16_f32 v78, v78, v79
	v_cvt_pk_bf16_f32 v79, v80, v81
	global_store_dwordx2 v[86:87], v[78:79], off
	s_waitcnt vmcnt(5)
	v_lshlrev_b32_e32 v170, 16, v174
	v_and_b32_e32 v171, 0xffff0000, v174
	v_lshlrev_b32_e32 v172, 16, v175
	v_and_b32_e32 v173, 0xffff0000, v175
	v_pk_fma_f32 v[76:77], v[76:77], v[172:173], v[178:179]
	v_pk_fma_f32 v[74:75], v[74:75], v[170:171], v[176:177]
	v_cvt_pk_bf16_f32 v74, v74, v75
	v_cvt_pk_bf16_f32 v75, v76, v77
	global_store_dwordx2 v[86:87], v[74:75], off offset:32
	s_waitcnt vmcnt(4)
	v_lshlrev_b32_e32 v170, 16, v180
	v_and_b32_e32 v171, 0xffff0000, v180
	v_lshlrev_b32_e32 v172, 16, v181
	v_and_b32_e32 v173, 0xffff0000, v181
	v_pk_fma_f32 v[72:73], v[72:73], v[172:173], v[184:185]
	v_pk_fma_f32 v[70:71], v[70:71], v[170:171], v[182:183]
	v_cvt_pk_bf16_f32 v70, v70, v71
	v_cvt_pk_bf16_f32 v71, v72, v73
	global_store_dwordx2 v[86:87], v[70:71], off offset:256
	s_waitcnt vmcnt(3)
	v_lshlrev_b32_e32 v170, 16, v186
	v_and_b32_e32 v171, 0xffff0000, v186
	v_lshlrev_b32_e32 v172, 16, v187
	v_and_b32_e32 v173, 0xffff0000, v187
	v_pk_fma_f32 v[68:69], v[68:69], v[172:173], v[190:191]
	v_pk_fma_f32 v[66:67], v[66:67], v[170:171], v[188:189]
	v_cvt_pk_bf16_f32 v66, v66, v67
	v_cvt_pk_bf16_f32 v67, v68, v69
	global_store_dwordx2 v[86:87], v[66:67], off offset:288
; __device__ __forceinline__ unsigned cvt_pk_bf16(float lo, float hi) { typedef float f2_ __attribute__((ext_vector_type(2))); typedef __bf16 b2_ __attribute__((ext_vector_type(2))); f2_ v = {lo, hi}; b2_ b = __builtin_convertvector(v, b2_); return __builtin_bit_cast(unsigned, b); }
;     DEV void apply(int r, int c, const f32x4 v) const { *(f32x4*)(PT + (size_t)r * DM + c) = v * ld_bf16x4(SG + (size_t)r * DM + c); }
; DEV f32x4 ld_bf16x4(const bf16* p) { const v2u w = *(const v2u*)p; return (f32x4){bflo(w.x), bfhi(w.x), bflo(w.y), bfhi(w.y)}; }
; DEV void st_bf16x4(bf16* p, const f32x4 v) { v2u w; w.x = pg8::cvt_pk_bf16(v[0], v[1]); w.y = pg8::cvt_pk_bf16(v[2], v[3]); *(v2u*)p = w; }
;     DEV void apply(int r, int c, const f32x4 v) const { st_bf16x4(MG + (size_t)r * DM + c, *(const f32x4*)(PT + (size_t)r * DM + c) + v * ld_bf16x4(SG + (size_t)r * DM + c)); }
;     DEV void operator()(const f32x4 (&acc)[2][2][4][2], const pg8::Unit& u, int wr, int wc, int fr_, int fq_) const { int fr = fr_, fq = fq_; asm volatile("" : "+v"(fr), "+v"(fq));
;         EPI_ALL({ apply(r, c, v); }) }
.LBB0_1844:
	s_or_b64 exec, exec, s[24:25]
	v_add_u32_e32 v66, 0x80, v144
	v_cmp_gt_i32_e32 vcc, s56, v66
	s_and_saveexec_b64 s[24:25], vcc
	s_cbranch_execz .LBB0_1846
	v_ashrrev_i32_e32 v67, 31, v66
	v_lshlrev_b64 v[70:71], 11, v[66:67]
	v_lshlrev_b64 v[72:73], 1, v[142:143]
	v_lshl_add_u64 v[68:69], s[6:7], 0, v[70:71]
	v_lshlrev_b64 v[66:67], 12, v[66:67]
	v_lshl_add_u64 v[74:75], v[68:69], 0, v[72:73]
	v_lshl_add_u64 v[66:67], s[8:9], 0, v[66:67]
	global_load_dwordx2 v[76:77], v[74:75], off
	v_lshl_add_u64 v[78:79], v[142:143], 2, v[66:67]
	global_load_dwordx4 v[66:69], v[78:79], off
	v_lshl_add_u64 v[70:71], s[10:11], 0, v[70:71]
	v_lshl_add_u64 v[70:71], v[70:71], 0, v[72:73]
	global_load_dwordx2 v[174:175], v[74:75], off offset:32
	global_load_dwordx4 v[176:179], v[78:79], off offset:64
	global_load_dwordx2 v[180:181], v[74:75], off offset:256
	global_load_dwordx4 v[182:185], v[78:79], off offset:512
	global_load_dwordx2 v[186:187], v[74:75], off offset:288
	global_load_dwordx4 v[188:191], v[78:79], off offset:576
	s_waitcnt vmcnt(6)
	v_lshlrev_b32_e32 v170, 16, v76
	v_and_b32_e32 v171, 0xffff0000, v76
	v_lshlrev_b32_e32 v172, 16, v77
	v_and_b32_e32 v173, 0xffff0000, v77
	v_pk_fma_f32 v[64:65], v[64:65], v[172:173], v[68:69]
	v_pk_fma_f32 v[62:63], v[62:63], v[170:171], v[66:67]
	v_cvt_pk_bf16_f32 v62, v62, v63
	v_cvt_pk_bf16_f32 v63, v64, v65
	global_store_dwordx2 v[70:71], v[62:63], off
	s_waitcnt vmcnt(5)
	v_lshlrev_b32_e32 v170, 16, v174
	v_and_b32_e32 v171, 0xffff0000, v174
	v_lshlrev_b32_e32 v172, 16, v175
	v_and_b32_e32 v173, 0xffff0000, v175
	v_pk_fma_f32 v[60:61], v[60:61], v[172:173], v[178:179]
	v_pk_fma_f32 v[58:59], v[58:59], v[170:171], v[176:177]
	v_cvt_pk_bf16_f32 v58, v58, v59
	v_cvt_pk_bf16_f32 v59, v60, v61
	global_store_dwordx2 v[70:71], v[58:59], off offset:32
	s_waitcnt vmcnt(4)
	v_lshlrev_b32_e32 v170, 16, v180
	v_and_b32_e32 v171, 0xffff0000, v180
	v_lshlrev_b32_e32 v172, 16, v181
	v_and_b32_e32 v173, 0xffff0000, v181
	v_pk_fma_f32 v[56:57], v[56:57], v[172:173], v[184:185]
	v_pk_fma_f32 v[54:55], v[54:55], v[170:171], v[182:183]
	v_cvt_pk_bf16_f32 v54, v54, v55
	v_cvt_pk_bf16_f32 v55, v56, v57
	global_store_dwordx2 v[70:71], v[54:55], off offset:256
	s_waitcnt vmcnt(3)
	v_lshlrev_b32_e32 v170, 16, v186
	v_and_b32_e32 v171, 0xffff0000, v186
	v_lshlrev_b32_e32 v172, 16, v187
	v_and_b32_e32 v173, 0xffff0000, v187
	v_pk_fma_f32 v[52:53], v[52:53], v[172:173], v[190:191]
	v_pk_fma_f32 v[50:51], v[50:51], v[170:171], v[188:189]
	v_cvt_pk_bf16_f32 v50, v50, v51
	v_cvt_pk_bf16_f32 v51, v52, v53
	global_store_dwordx2 v[70:71], v[50:51], off offset:288
.LBB0_1846:
	s_or_b64 exec, exec, s[24:25]
	v_add_u32_e32 v50, 0x90, v144
	v_cmp_gt_i32_e32 vcc, s56, v50
	s_and_saveexec_b64 s[24:25], vcc
	s_cbranch_execz .LBB0_1848
	v_ashrrev_i32_e32 v51, 31, v50
	v_lshlrev_b64 v[54:55], 11, v[50:51]
	v_lshlrev_b64 v[56:57], 1, v[142:143]
	v_lshl_add_u64 v[52:53], s[6:7], 0, v[54:55]
	v_lshlrev_b64 v[50:51], 12, v[50:51]
	v_lshl_add_u64 v[58:59], v[52:53], 0, v[56:57]
	v_lshl_add_u64 v[50:51], s[8:9], 0, v[50:51]
	global_load_dwordx2 v[60:61], v[58:59], off
	v_lshl_add_u64 v[62:63], v[142:143], 2, v[50:51]
	global_load_dwordx4 v[50:53], v[62:63], off
	v_lshl_add_u64 v[54:55], s[10:11], 0, v[54:55]
	v_lshl_add_u64 v[54:55], v[54:55], 0, v[56:57]
	global_load_dwordx2 v[174:175], v[58:59], off offset:32
	global_load_dwordx4 v[176:179], v[62:63], off offset:64
	global_load_dwordx2 v[180:181], v[58:59], off offset:256
	global_load_dwordx4 v[182:185], v[62:63], off offset:512
	global_load_dwordx2 v[186:187], v[58:59], off offset:288
	global_load_dwordx4 v[188:191], v[62:63], off offset:576
	s_waitcnt vmcnt(6)
	v_lshlrev_b32_e32 v170, 16, v60
	v_and_b32_e32 v171, 0xffff0000, v60
	v_lshlrev_b32_e32 v172, 16, v61
	v_and_b32_e32 v173, 0xffff0000, v61
	v_pk_fma_f32 v[48:49], v[48:49], v[172:173], v[52:53]
	v_pk_fma_f32 v[46:47], v[46:47], v[170:171], v[50:51]
	v_cvt_pk_bf16_f32 v46, v46, v47
	v_cvt_pk_bf16_f32 v47, v48, v49
	global_store_dwordx2 v[54:55], v[46:47], off
	s_waitcnt vmcnt(5)
	v_lshlrev_b32_e32 v170, 16, v174
	v_and_b32_e32 v171, 0xffff0000, v174
	v_lshlrev_b32_e32 v172, 16, v175
	v_and_b32_e32 v173, 0xffff0000, v175
	v_pk_fma_f32 v[44:45], v[44:45], v[172:173], v[178:179]
	v_pk_fma_f32 v[42:43], v[42:43], v[170:171], v[176:177]
	v_cvt_pk_bf16_f32 v42, v42, v43
	v_cvt_pk_bf16_f32 v43, v44, v45
	global_store_dwordx2 v[54:55], v[42:43], off offset:32
	s_waitcnt vmcnt(4)
	v_lshlrev_b32_e32 v170, 16, v180
	v_and_b32_e32 v171, 0xffff0000, v180
	v_lshlrev_b32_e32 v172, 16, v181
	v_and_b32_e32 v173, 0xffff0000, v181
	v_pk_fma_f32 v[40:41], v[40:41], v[172:173], v[184:185]
	v_pk_fma_f32 v[38:39], v[38:39], v[170:171], v[182:183]
	v_cvt_pk_bf16_f32 v38, v38, v39
	v_cvt_pk_bf16_f32 v39, v40, v41
	global_store_dwordx2 v[54:55], v[38:39], off offset:256
	s_waitcnt vmcnt(3)
	v_lshlrev_b32_e32 v170, 16, v186
	v_and_b32_e32 v171, 0xffff0000, v186
	v_lshlrev_b32_e32 v172, 16, v187
	v_and_b32_e32 v173, 0xffff0000, v187
	v_pk_fma_f32 v[36:37], v[36:37], v[172:173], v[190:191]
	v_pk_fma_f32 v[34:35], v[34:35], v[170:171], v[188:189]
	v_cvt_pk_bf16_f32 v34, v34, v35
	v_cvt_pk_bf16_f32 v35, v36, v37
	global_store_dwordx2 v[54:55], v[34:35], off offset:288
; __device__ __forceinline__ unsigned cvt_pk_bf16(float lo, float hi) { typedef float f2_ __attribute__((ext_vector_type(2))); typedef __bf16 b2_ __attribute__((ext_vector_type(2))); f2_ v = {lo, hi}; b2_ b = __builtin_convertvector(v, b2_); return __builtin_bit_cast(unsigned, b); }
;     DEV void apply(int r, int c, const f32x4 v) const { *(f32x4*)(PT + (size_t)r * DM + c) = v * ld_bf16x4(SG + (size_t)r * DM + c); }
; DEV f32x4 ld_bf16x4(const bf16* p) { const v2u w = *(const v2u*)p; return (f32x4){bflo(w.x), bfhi(w.x), bflo(w.y), bfhi(w.y)}; }
; DEV void st_bf16x4(bf16* p, const f32x4 v) { v2u w; w.x = pg8::cvt_pk_bf16(v[0], v[1]); w.y = pg8::cvt_pk_bf16(v[2], v[3]); *(v2u*)p = w; }
;     DEV void apply(int r, int c, const f32x4 v) const { st_bf16x4(MG + (size_t)r * DM + c, *(const f32x4*)(PT + (size_t)r * DM + c) + v * ld_bf16x4(SG + (size_t)r * DM + c)); }
;     DEV void operator()(const f32x4 (&acc)[2][2][4][2], const pg8::Unit& u, int wr, int wc, int fr_, int fq_) const { int fr = fr_, fq = fq_; asm volatile("" : "+v"(fr), "+v"(fq));
;         EPI_ALL({ apply(r, c, v); }) }
.LBB0_1848:
	s_or_b64 exec, exec, s[24:25]
	v_add_u32_e32 v34, 0xa0, v144
	v_cmp_gt_i32_e32 vcc, s56, v34
	s_and_saveexec_b64 s[24:25], vcc
	s_cbranch_execz .LBB0_1850
	v_ashrrev_i32_e32 v35, 31, v34
	v_lshlrev_b64 v[38:39], 11, v[34:35]
	v_lshlrev_b64 v[40:41], 1, v[142:143]
	v_lshl_add_u64 v[36:37], s[6:7], 0, v[38:39]
	v_lshlrev_b64 v[34:35], 12, v[34:35]
	v_lshl_add_u64 v[42:43], v[36:37], 0, v[40:41]
	v_lshl_add_u64 v[34:35], s[8:9], 0, v[34:35]
	global_load_dwordx2 v[44:45], v[42:43], off
	v_lshl_add_u64 v[46:47], v[142:143], 2, v[34:35]
	global_load_dwordx4 v[34:37], v[46:47], off
	v_lshl_add_u64 v[38:39], s[10:11], 0, v[38:39]
	v_lshl_add_u64 v[38:39], v[38:39], 0, v[40:41]
	global_load_dwordx2 v[174:175], v[42:43], off offset:32
	global_load_dwordx4 v[176:179], v[46:47], off offset:64
	global_load_dwordx2 v[180:181], v[42:43], off offset:256
	global_load_dwordx4 v[182:185], v[46:47], off offset:512
	global_load_dwordx2 v[186:187], v[42:43], off offset:288
	global_load_dwordx4 v[188:191], v[46:47], off offset:576
	s_waitcnt vmcnt(6)
	v_lshlrev_b32_e32 v170, 16, v44
	v_and_b32_e32 v171, 0xffff0000, v44
	v_lshlrev_b32_e32 v172, 16, v45
	v_and_b32_e32 v173, 0xffff0000, v45
	v_pk_fma_f32 v[32:33], v[32:33], v[172:173], v[36:37]
	v_pk_fma_f32 v[30:31], v[30:31], v[170:171], v[34:35]
	v_cvt_pk_bf16_f32 v30, v30, v31
	v_cvt_pk_bf16_f32 v31, v32, v33
	global_store_dwordx2 v[38:39], v[30:31], off
	s_waitcnt vmcnt(5)
	v_lshlrev_b32_e32 v170, 16, v174
	v_and_b32_e32 v171, 0xffff0000, v174
	v_lshlrev_b32_e32 v172, 16, v175
	v_and_b32_e32 v173, 0xffff0000, v175
	v_pk_fma_f32 v[28:29], v[28:29], v[172:173], v[178:179]
	v_pk_fma_f32 v[26:27], v[26:27], v[170:171], v[176:177]
	v_cvt_pk_bf16_f32 v26, v26, v27
	v_cvt_pk_bf16_f32 v27, v28, v29
	global_store_dwordx2 v[38:39], v[26:27], off offset:32
	s_waitcnt vmcnt(4)
	v_lshlrev_b32_e32 v170, 16, v180
	v_and_b32_e32 v171, 0xffff0000, v180
	v_lshlrev_b32_e32 v172, 16, v181
	v_and_b32_e32 v173, 0xffff0000, v181
	v_pk_fma_f32 v[24:25], v[24:25], v[172:173], v[184:185]
	v_pk_fma_f32 v[22:23], v[22:23], v[170:171], v[182:183]
	v_cvt_pk_bf16_f32 v22, v22, v23
	v_cvt_pk_bf16_f32 v23, v24, v25
	global_store_dwordx2 v[38:39], v[22:23], off offset:256
	s_waitcnt vmcnt(3)
	v_lshlrev_b32_e32 v170, 16, v186
	v_and_b32_e32 v171, 0xffff0000, v186
	v_lshlrev_b32_e32 v172, 16, v187
	v_and_b32_e32 v173, 0xffff0000, v187
	v_pk_fma_f32 v[20:21], v[20:21], v[172:173], v[190:191]
	v_pk_fma_f32 v[18:19], v[18:19], v[170:171], v[188:189]
	v_cvt_pk_bf16_f32 v18, v18, v19
	v_cvt_pk_bf16_f32 v19, v20, v21
	global_store_dwordx2 v[38:39], v[18:19], off offset:288
.LBB0_1850:
	s_or_b64 exec, exec, s[24:25]
	v_add_u32_e32 v18, 0xb0, v144
	v_cmp_gt_i32_e32 vcc, s56, v18
	s_and_saveexec_b64 s[24:25], vcc
	s_cbranch_execz .LBB0_1852
	v_ashrrev_i32_e32 v19, 31, v18
	v_lshlrev_b64 v[22:23], 11, v[18:19]
	v_lshlrev_b64 v[24:25], 1, v[142:143]
	v_lshl_add_u64 v[20:21], s[6:7], 0, v[22:23]
	v_lshlrev_b64 v[18:19], 12, v[18:19]
	v_lshl_add_u64 v[26:27], v[20:21], 0, v[24:25]
	v_lshl_add_u64 v[18:19], s[8:9], 0, v[18:19]
	global_load_dwordx2 v[28:29], v[26:27], off
	v_lshl_add_u64 v[30:31], v[142:143], 2, v[18:19]
	global_load_dwordx4 v[18:21], v[30:31], off
	v_lshl_add_u64 v[22:23], s[10:11], 0, v[22:23]
	v_lshl_add_u64 v[22:23], v[22:23], 0, v[24:25]
	global_load_dwordx2 v[174:175], v[26:27], off offset:32
	global_load_dwordx4 v[176:179], v[30:31], off offset:64
	global_load_dwordx2 v[180:181], v[26:27], off offset:256
	global_load_dwordx4 v[182:185], v[30:31], off offset:512
	global_load_dwordx2 v[186:187], v[26:27], off offset:288
	global_load_dwordx4 v[188:191], v[30:31], off offset:576
	s_waitcnt vmcnt(6)
	v_lshlrev_b32_e32 v170, 16, v28
	v_and_b32_e32 v171, 0xffff0000, v28
	v_lshlrev_b32_e32 v172, 16, v29
	v_and_b32_e32 v173, 0xffff0000, v29
	v_pk_fma_f32 v[16:17], v[16:17], v[172:173], v[20:21]
	v_pk_fma_f32 v[14:15], v[14:15], v[170:171], v[18:19]
	v_cvt_pk_bf16_f32 v14, v14, v15
	v_cvt_pk_bf16_f32 v15, v16, v17
	global_store_dwordx2 v[22:23], v[14:15], off
	s_waitcnt vmcnt(5)
	v_lshlrev_b32_e32 v170, 16, v174
	v_and_b32_e32 v171, 0xffff0000, v174
	v_lshlrev_b32_e32 v172, 16, v175
	v_and_b32_e32 v173, 0xffff0000, v175
	v_pk_fma_f32 v[12:13], v[12:13], v[172:173], v[178:179]
	v_pk_fma_f32 v[10:11], v[10:11], v[170:171], v[176:177]
	v_cvt_pk_bf16_f32 v10, v10, v11
	v_cvt_pk_bf16_f32 v11, v12, v13
	global_store_dwordx2 v[22:23], v[10:11], off offset:32
	s_waitcnt vmcnt(4)
	v_lshlrev_b32_e32 v170, 16, v180
	v_and_b32_e32 v171, 0xffff0000, v180
	v_lshlrev_b32_e32 v172, 16, v181
	v_and_b32_e32 v173, 0xffff0000, v181
	v_pk_fma_f32 v[8:9], v[8:9], v[172:173], v[184:185]
	v_pk_fma_f32 v[6:7], v[6:7], v[170:171], v[182:183]
	v_cvt_pk_bf16_f32 v6, v6, v7
	v_cvt_pk_bf16_f32 v7, v8, v9
	global_store_dwordx2 v[22:23], v[6:7], off offset:256
	s_waitcnt vmcnt(3)
	v_lshlrev_b32_e32 v170, 16, v186
	v_and_b32_e32 v171, 0xffff0000, v186
	v_lshlrev_b32_e32 v172, 16, v187
	v_and_b32_e32 v173, 0xffff0000, v187
	v_pk_fma_f32 v[4:5], v[4:5], v[172:173], v[190:191]
	v_pk_fma_f32 v[2:3], v[2:3], v[170:171], v[188:189]
	v_cvt_pk_bf16_f32 v2, v2, v3
	v_cvt_pk_bf16_f32 v3, v4, v5
	global_store_dwordx2 v[22:23], v[2:3], off offset:288

;     DEV void apply(int r, int c, const f32x4 v) const { *(f32x4*)(PT + (size_t)r * DM + c) = v * ld_bf16x4(SG + (size_t)r * DM + c); }
;     DEV void apply(int r, int c, const f32x4 v) const { st_bf16x4(MG + (size_t)r * DM + c, *(const f32x4*)(PT + (size_t)r * DM + c) + v * ld_bf16x4(SG + (size_t)r * DM + c)); }
;     DEV void operator()(const f32x4 (&acc)[2][2][4][2], const pg8::Unit& u, int wr, int wc, int fr_, int fq_) const { int fr = fr_, fq = fq_; asm volatile("" : "+v"(fr), "+v"(fq));
;         EPI_ALL({ apply(r, c, v); }) }
.LBB0_1940:
	s_lshl_b32 s17, s22, 8
	v_mov_b32_e32 v134, v1
	v_mov_b32_e32 v144, v148
	s_add_i32 s17, s17, s42
	s_nop 0
	v_add_u32_e32 v146, s17, v134
	s_lshl_b32 s17, s24, 8
	s_or_b32 s17, s17, s43
	v_lshl_add_u32 v144, v144, 2, s17
	v_cmp_gt_i32_e32 vcc, s54, v146
	v_ashrrev_i32_e32 v145, 31, v144
	s_and_saveexec_b64 s[22:23], vcc
	s_cbranch_execz .LBB0_1942
	v_ashrrev_i32_e32 v147, 31, v146
	v_add_u32_e32 v134, 0xffffc000, v146
	v_cmp_lt_i32_e32 vcc, s55, v146
	v_lshlrev_b64 v[158:159], 12, v[146:147]
	v_lshlrev_b64 v[154:155], 12, v[134:135]
	v_lshl_add_u64 v[156:157], s[44:45], 0, v[158:159]
	v_lshl_add_u64 v[154:155], s[46:47], 0, v[154:155]
	s_and_b64 vcc, s[14:15], vcc
	v_cndmask_b32_e32 v155, v157, v155, vcc
	v_cndmask_b32_e32 v154, v156, v154, vcc
	v_lshlrev_b64 v[162:163], 2, v[144:145]
	v_lshl_add_u64 v[164:165], v[154:155], 0, v[162:163]
	global_load_dwordx4 v[154:157], v[164:165], off
	v_mov_b32_e32 v147, v135
	v_lshlrev_b64 v[160:161], 12, v[146:147]
	v_cndmask_b32_e32 v159, v159, v161, vcc
	v_cndmask_b32_e32 v158, v158, v160, vcc
	v_lshl_add_u64 v[158:159], s[6:7], 0, v[158:159]
	v_lshl_add_u64 v[158:159], v[158:159], 0, v[162:163]
	global_load_dwordx4 v[174:177], v[164:165], off offset:64
	global_load_dwordx4 v[178:181], v[164:165], off offset:512
	global_load_dwordx4 v[182:185], v[164:165], off offset:576
	s_waitcnt vmcnt(3)
	v_pk_add_f32 v[128:129], v[128:129], v[156:157]
	v_pk_add_f32 v[126:127], v[126:127], v[154:155]
	global_store_dwordx4 v[158:159], v[126:129], off
	s_waitcnt vmcnt(3)
	v_pk_add_f32 v[124:125], v[124:125], v[176:177]
	v_pk_add_f32 v[122:123], v[122:123], v[174:175]
	global_store_dwordx4 v[158:159], v[122:125], off offset:64
	s_waitcnt vmcnt(3)
	v_pk_add_f32 v[120:121], v[120:121], v[180:181]
	v_pk_add_f32 v[118:119], v[118:119], v[178:179]
	global_store_dwordx4 v[158:159], v[118:121], off offset:512
	s_waitcnt vmcnt(3)
	v_pk_add_f32 v[116:117], v[116:117], v[184:185]
	v_pk_add_f32 v[114:115], v[114:115], v[182:183]
	global_store_dwordx4 v[158:159], v[114:117], off offset:576
.LBB0_1942:
	s_or_b64 exec, exec, s[22:23]
	s_nop 0
	v_add_u32_e32 v114, 16, v146
	v_cmp_gt_i32_e32 vcc, s54, v114
	s_and_saveexec_b64 s[22:23], vcc
	s_cbranch_execz .LBB0_1944
	v_ashrrev_i32_e32 v115, 31, v114
	v_add_u32_e32 v134, 0xffffc010, v146
	v_cmp_lt_i32_e32 vcc, s55, v114
	v_lshlrev_b64 v[118:119], 12, v[114:115]
	v_lshlrev_b64 v[116:117], 12, v[134:135]
	v_mov_b32_e32 v115, v135
	v_lshlrev_b64 v[120:121], 12, v[114:115]
	v_lshl_add_u64 v[114:115], s[44:45], 0, v[118:119]
	v_lshl_add_u64 v[116:117], s[46:47], 0, v[116:117]
	s_and_b64 vcc, s[14:15], vcc
	v_cndmask_b32_e32 v115, v115, v117, vcc
	v_cndmask_b32_e32 v114, v114, v116, vcc
	v_lshlrev_b64 v[122:123], 2, v[144:145]
	v_lshl_add_u64 v[124:125], v[114:115], 0, v[122:123]
	global_load_dwordx4 v[114:117], v[124:125], off
	v_cndmask_b32_e32 v119, v119, v121, vcc
	v_cndmask_b32_e32 v118, v118, v120, vcc
	v_lshl_add_u64 v[118:119], s[6:7], 0, v[118:119]
	v_lshl_add_u64 v[118:119], v[118:119], 0, v[122:123]
	global_load_dwordx4 v[174:177], v[124:125], off offset:64
	global_load_dwordx4 v[178:181], v[124:125], off offset:512
	global_load_dwordx4 v[182:185], v[124:125], off offset:576
	s_waitcnt vmcnt(3)
	v_pk_add_f32 v[112:113], v[112:113], v[116:117]
	v_pk_add_f32 v[110:111], v[110:111], v[114:115]
	global_store_dwordx4 v[118:119], v[110:113], off
	s_waitcnt vmcnt(3)
	v_pk_add_f32 v[108:109], v[108:109], v[176:177]
	v_pk_add_f32 v[106:107], v[106:107], v[174:175]
	global_store_dwordx4 v[118:119], v[106:109], off offset:64
	s_waitcnt vmcnt(3)
	v_pk_add_f32 v[104:105], v[104:105], v[180:181]
	v_pk_add_f32 v[102:103], v[102:103], v[178:179]
	global_store_dwordx4 v[118:119], v[102:105], off offset:512
	s_waitcnt vmcnt(3)
	v_pk_add_f32 v[100:101], v[100:101], v[184:185]
	v_pk_add_f32 v[98:99], v[98:99], v[182:183]
	global_store_dwordx4 v[118:119], v[98:101], off offset:576
.LBB0_1944:
	s_or_b64 exec, exec, s[22:23]
	s_nop 0
	v_add_u32_e32 v98, 32, v146
	v_cmp_gt_i32_e32 vcc, s54, v98
	s_and_saveexec_b64 s[22:23], vcc
	s_cbranch_execz .LBB0_1946
	v_ashrrev_i32_e32 v99, 31, v98
	v_add_u32_e32 v134, 0xffffc020, v146
	v_cmp_lt_i32_e32 vcc, s55, v98
	v_lshlrev_b64 v[102:103], 12, v[98:99]
	v_lshlrev_b64 v[100:101], 12, v[134:135]
	v_mov_b32_e32 v99, v135
	v_lshlrev_b64 v[104:105], 12, v[98:99]
	v_lshl_add_u64 v[98:99], s[44:45], 0, v[102:103]
	v_lshl_add_u64 v[100:101], s[46:47], 0, v[100:101]
	s_and_b64 vcc, s[14:15], vcc
	v_cndmask_b32_e32 v99, v99, v101, vcc
	v_cndmask_b32_e32 v98, v98, v100, vcc
	v_lshlrev_b64 v[106:107], 2, v[144:145]
	v_lshl_add_u64 v[108:109], v[98:99], 0, v[106:107]
	global_load_dwordx4 v[98:101], v[108:109], off
	v_cndmask_b32_e32 v103, v103, v105, vcc
	v_cndmask_b32_e32 v102, v102, v104, vcc
	v_lshl_add_u64 v[102:103], s[6:7], 0, v[102:103]
	v_lshl_add_u64 v[102:103], v[102:103], 0, v[106:107]
	global_load_dwordx4 v[174:177], v[108:109], off offset:64
	global_load_dwordx4 v[178:181], v[108:109], off offset:512
	global_load_dwordx4 v[182:185], v[108:109], off offset:576
	s_waitcnt vmcnt(3)
	v_pk_add_f32 v[96:97], v[96:97], v[100:101]
	v_pk_add_f32 v[94:95], v[94:95], v[98:99]
	global_store_dwordx4 v[102:103], v[94:97], off
	s_waitcnt vmcnt(3)
	v_pk_add_f32 v[92:93], v[92:93], v[176:177]
	v_pk_add_f32 v[90:91], v[90:91], v[174:175]
	global_store_dwordx4 v[102:103], v[90:93], off offset:64
	s_waitcnt vmcnt(3)
	v_pk_add_f32 v[88:89], v[88:89], v[180:181]
	v_pk_add_f32 v[86:87], v[86:87], v[178:179]
	global_store_dwordx4 v[102:103], v[86:89], off offset:512
	s_waitcnt vmcnt(3)
	v_pk_add_f32 v[84:85], v[84:85], v[184:185]
	v_pk_add_f32 v[82:83], v[82:83], v[182:183]
	global_store_dwordx4 v[102:103], v[82:85], off offset:576
;     DEV void apply(int r, int c, const f32x4 v) const { *(f32x4*)(PT + (size_t)r * DM + c) = v * ld_bf16x4(SG + (size_t)r * DM + c); }
;     DEV void apply(int r, int c, const f32x4 v) const { st_bf16x4(MG + (size_t)r * DM + c, *(const f32x4*)(PT + (size_t)r * DM + c) + v * ld_bf16x4(SG + (size_t)r * DM + c)); }
;     DEV void operator()(const f32x4 (&acc)[2][2][4][2], const pg8::Unit& u, int wr, int wc, int fr_, int fq_) const { int fr = fr_, fq = fq_; asm volatile("" : "+v"(fr), "+v"(fq));
;         EPI_ALL({ apply(r, c, v); }) }
.LBB0_1946:
	s_or_b64 exec, exec, s[22:23]
	s_nop 0
	v_add_u32_e32 v82, 48, v146
	v_cmp_gt_i32_e32 vcc, s54, v82
	s_and_saveexec_b64 s[22:23], vcc
	s_cbranch_execz .LBB0_1948
	v_ashrrev_i32_e32 v83, 31, v82
	v_add_u32_e32 v134, 0xffffc030, v146
	v_cmp_lt_i32_e32 vcc, s55, v82
	v_lshlrev_b64 v[86:87], 12, v[82:83]
	v_lshlrev_b64 v[84:85], 12, v[134:135]
	v_mov_b32_e32 v83, v135
	v_lshlrev_b64 v[88:89], 12, v[82:83]
	v_lshl_add_u64 v[82:83], s[44:45], 0, v[86:87]
	v_lshl_add_u64 v[84:85], s[46:47], 0, v[84:85]
	s_and_b64 vcc, s[14:15], vcc
	v_cndmask_b32_e32 v83, v83, v85, vcc
	v_cndmask_b32_e32 v82, v82, v84, vcc
	v_lshlrev_b64 v[90:91], 2, v[144:145]
	v_lshl_add_u64 v[92:93], v[82:83], 0, v[90:91]
	global_load_dwordx4 v[82:85], v[92:93], off
	v_cndmask_b32_e32 v87, v87, v89, vcc
	v_cndmask_b32_e32 v86, v86, v88, vcc
	v_lshl_add_u64 v[86:87], s[6:7], 0, v[86:87]
	v_lshl_add_u64 v[86:87], v[86:87], 0, v[90:91]
	global_load_dwordx4 v[174:177], v[92:93], off offset:64
	global_load_dwordx4 v[178:181], v[92:93], off offset:512
	global_load_dwordx4 v[182:185], v[92:93], off offset:576
	s_waitcnt vmcnt(3)
	v_pk_add_f32 v[80:81], v[80:81], v[84:85]
	v_pk_add_f32 v[78:79], v[78:79], v[82:83]
	global_store_dwordx4 v[86:87], v[78:81], off
	s_waitcnt vmcnt(3)
	v_pk_add_f32 v[76:77], v[76:77], v[176:177]
	v_pk_add_f32 v[74:75], v[74:75], v[174:175]
	global_store_dwordx4 v[86:87], v[74:77], off offset:64
	s_waitcnt vmcnt(3)
	v_pk_add_f32 v[72:73], v[72:73], v[180:181]
	v_pk_add_f32 v[70:71], v[70:71], v[178:179]
	global_store_dwordx4 v[86:87], v[70:73], off offset:512
	s_waitcnt vmcnt(3)
	v_pk_add_f32 v[68:69], v[68:69], v[184:185]
	v_pk_add_f32 v[66:67], v[66:67], v[182:183]
	global_store_dwordx4 v[86:87], v[66:69], off offset:576
.LBB0_1948:
	s_or_b64 exec, exec, s[22:23]
	s_nop 0
	v_add_u32_e32 v66, 0x80, v146
	v_cmp_gt_i32_e32 vcc, s54, v66
	s_and_saveexec_b64 s[22:23], vcc
	s_cbranch_execz .LBB0_1950
	v_ashrrev_i32_e32 v67, 31, v66
	v_add_u32_e32 v134, 0xffffc080, v146
	v_cmp_lt_i32_e32 vcc, s55, v66
	v_lshlrev_b64 v[70:71], 12, v[66:67]
	v_lshlrev_b64 v[68:69], 12, v[134:135]
	v_mov_b32_e32 v67, v135
	v_lshlrev_b64 v[72:73], 12, v[66:67]
	v_lshl_add_u64 v[66:67], s[44:45], 0, v[70:71]
	v_lshl_add_u64 v[68:69], s[46:47], 0, v[68:69]
	s_and_b64 vcc, s[14:15], vcc
	v_cndmask_b32_e32 v67, v67, v69, vcc
	v_cndmask_b32_e32 v66, v66, v68, vcc
	v_lshlrev_b64 v[74:75], 2, v[144:145]
	v_lshl_add_u64 v[76:77], v[66:67], 0, v[74:75]
	global_load_dwordx4 v[66:69], v[76:77], off
	v_cndmask_b32_e32 v71, v71, v73, vcc
	v_cndmask_b32_e32 v70, v70, v72, vcc
	v_lshl_add_u64 v[70:71], s[6:7], 0, v[70:71]
	v_lshl_add_u64 v[70:71], v[70:71], 0, v[74:75]
	global_load_dwordx4 v[174:177], v[76:77], off offset:64
	global_load_dwordx4 v[178:181], v[76:77], off offset:512
	global_load_dwordx4 v[182:185], v[76:77], off offset:576
	s_waitcnt vmcnt(3)
	v_pk_add_f32 v[64:65], v[64:65], v[68:69]
	v_pk_add_f32 v[62:63], v[62:63], v[66:67]
	global_store_dwordx4 v[70:71], v[62:65], off
	s_waitcnt vmcnt(3)
	v_pk_add_f32 v[60:61], v[60:61], v[176:177]
	v_pk_add_f32 v[58:59], v[58:59], v[174:175]
	global_store_dwordx4 v[70:71], v[58:61], off offset:64
	s_waitcnt vmcnt(3)
	v_pk_add_f32 v[56:57], v[56:57], v[180:181]
	v_pk_add_f32 v[54:55], v[54:55], v[178:179]
	global_store_dwordx4 v[70:71], v[54:57], off offset:512
	s_waitcnt vmcnt(3)
	v_pk_add_f32 v[52:53], v[52:53], v[184:185]
	v_pk_add_f32 v[50:51], v[50:51], v[182:183]
	global_store_dwordx4 v[70:71], v[50:53], off offset:576
;     DEV void apply(int r, int c, const f32x4 v) const { *(f32x4*)(PT + (size_t)r * DM + c) = v * ld_bf16x4(SG + (size_t)r * DM + c); }
;     DEV void apply(int r, int c, const f32x4 v) const { st_bf16x4(MG + (size_t)r * DM + c, *(const f32x4*)(PT + (size_t)r * DM + c) + v * ld_bf16x4(SG + (size_t)r * DM + c)); }
;     DEV void operator()(const f32x4 (&acc)[2][2][4][2], const pg8::Unit& u, int wr, int wc, int fr_, int fq_) const { int fr = fr_, fq = fq_; asm volatile("" : "+v"(fr), "+v"(fq));
;         EPI_ALL({ apply(r, c, v); }) }
.LBB0_1950:
	s_or_b64 exec, exec, s[22:23]
	s_nop 0
	v_add_u32_e32 v50, 0x90, v146
	v_cmp_gt_i32_e32 vcc, s54, v50
	s_and_saveexec_b64 s[22:23], vcc
	s_cbranch_execz .LBB0_1952
	v_ashrrev_i32_e32 v51, 31, v50
	v_add_u32_e32 v134, 0xffffc090, v146
	v_cmp_lt_i32_e32 vcc, s55, v50
	v_lshlrev_b64 v[54:55], 12, v[50:51]
	v_lshlrev_b64 v[52:53], 12, v[134:135]
	v_mov_b32_e32 v51, v135
	v_lshlrev_b64 v[56:57], 12, v[50:51]
	v_lshl_add_u64 v[50:51], s[44:45], 0, v[54:55]
	v_lshl_add_u64 v[52:53], s[46:47], 0, v[52:53]
	s_and_b64 vcc, s[14:15], vcc
	v_cndmask_b32_e32 v51, v51, v53, vcc
	v_cndmask_b32_e32 v50, v50, v52, vcc
	v_lshlrev_b64 v[58:59], 2, v[144:145]
	v_lshl_add_u64 v[60:61], v[50:51], 0, v[58:59]
	global_load_dwordx4 v[50:53], v[60:61], off
	v_cndmask_b32_e32 v55, v55, v57, vcc
	v_cndmask_b32_e32 v54, v54, v56, vcc
	v_lshl_add_u64 v[54:55], s[6:7], 0, v[54:55]
	v_lshl_add_u64 v[54:55], v[54:55], 0, v[58:59]
	global_load_dwordx4 v[174:177], v[60:61], off offset:64
	global_load_dwordx4 v[178:181], v[60:61], off offset:512
	global_load_dwordx4 v[182:185], v[60:61], off offset:576
	s_waitcnt vmcnt(3)
	v_pk_add_f32 v[48:49], v[48:49], v[52:53]
	v_pk_add_f32 v[46:47], v[46:47], v[50:51]
	global_store_dwordx4 v[54:55], v[46:49], off
	s_waitcnt vmcnt(3)
	v_pk_add_f32 v[44:45], v[44:45], v[176:177]
	v_pk_add_f32 v[42:43], v[42:43], v[174:175]
	global_store_dwordx4 v[54:55], v[42:45], off offset:64
	s_waitcnt vmcnt(3)
	v_pk_add_f32 v[40:41], v[40:41], v[180:181]
	v_pk_add_f32 v[38:39], v[38:39], v[178:179]
	global_store_dwordx4 v[54:55], v[38:41], off offset:512
	s_waitcnt vmcnt(3)
	v_pk_add_f32 v[36:37], v[36:37], v[184:185]
	v_pk_add_f32 v[34:35], v[34:35], v[182:183]
	global_store_dwordx4 v[54:55], v[34:37], off offset:576
.LBB0_1952:
	s_or_b64 exec, exec, s[22:23]
	s_nop 0
	v_add_u32_e32 v34, 0xa0, v146
	v_cmp_gt_i32_e32 vcc, s54, v34
	s_and_saveexec_b64 s[22:23], vcc
	s_cbranch_execz .LBB0_1954
	v_ashrrev_i32_e32 v35, 31, v34
	v_add_u32_e32 v134, 0xffffc0a0, v146
	v_cmp_lt_i32_e32 vcc, s55, v34
	v_lshlrev_b64 v[38:39], 12, v[34:35]
	v_lshlrev_b64 v[36:37], 12, v[134:135]
	v_mov_b32_e32 v35, v135
	v_lshlrev_b64 v[40:41], 12, v[34:35]
	v_lshl_add_u64 v[34:35], s[44:45], 0, v[38:39]
	v_lshl_add_u64 v[36:37], s[46:47], 0, v[36:37]
	s_and_b64 vcc, s[14:15], vcc
	v_cndmask_b32_e32 v35, v35, v37, vcc
	v_cndmask_b32_e32 v34, v34, v36, vcc
	v_lshlrev_b64 v[42:43], 2, v[144:145]
	v_lshl_add_u64 v[44:45], v[34:35], 0, v[42:43]
	global_load_dwordx4 v[34:37], v[44:45], off
	v_cndmask_b32_e32 v39, v39, v41, vcc
	v_cndmask_b32_e32 v38, v38, v40, vcc
	v_lshl_add_u64 v[38:39], s[6:7], 0, v[38:39]
	v_lshl_add_u64 v[38:39], v[38:39], 0, v[42:43]
	global_load_dwordx4 v[174:177], v[44:45], off offset:64
	global_load_dwordx4 v[178:181], v[44:45], off offset:512
	global_load_dwordx4 v[182:185], v[44:45], off offset:576
	s_waitcnt vmcnt(3)
	v_pk_add_f32 v[32:33], v[32:33], v[36:37]
	v_pk_add_f32 v[30:31], v[30:31], v[34:35]
	global_store_dwordx4 v[38:39], v[30:33], off
	s_waitcnt vmcnt(3)
	v_pk_add_f32 v[28:29], v[28:29], v[176:177]
	v_pk_add_f32 v[26:27], v[26:27], v[174:175]
	global_store_dwordx4 v[38:39], v[26:29], off offset:64
	s_waitcnt vmcnt(3)
	v_pk_add_f32 v[24:25], v[24:25], v[180:181]
	v_pk_add_f32 v[22:23], v[22:23], v[178:179]
	global_store_dwordx4 v[38:39], v[22:25], off offset:512
	s_waitcnt vmcnt(3)
	v_pk_add_f32 v[20:21], v[20:21], v[184:185]
	v_pk_add_f32 v[18:19], v[18:19], v[182:183]
	global_store_dwordx4 v[38:39], v[18:21], off offset:576
.LBB0_1954:
	s_or_b64 exec, exec, s[22:23]
	s_nop 0
	v_add_u32_e32 v18, 0xb0, v146
	v_cmp_gt_i32_e32 vcc, s54, v18
	s_and_saveexec_b64 s[22:23], vcc
	s_cbranch_execz .LBB0_1956
	v_ashrrev_i32_e32 v19, 31, v18
	v_add_u32_e32 v134, 0xffffc0b0, v146
	v_cmp_lt_i32_e32 vcc, s55, v18
	v_lshlrev_b64 v[22:23], 12, v[18:19]
	v_lshlrev_b64 v[20:21], 12, v[134:135]
	v_mov_b32_e32 v19, v135
	v_lshlrev_b64 v[24:25], 12, v[18:19]
	v_lshl_add_u64 v[18:19], s[44:45], 0, v[22:23]
	v_lshl_add_u64 v[20:21], s[46:47], 0, v[20:21]
	s_and_b64 vcc, s[14:15], vcc
	v_cndmask_b32_e32 v19, v19, v21, vcc
	v_cndmask_b32_e32 v18, v18, v20, vcc
	v_lshlrev_b64 v[26:27], 2, v[144:145]
	v_lshl_add_u64 v[28:29], v[18:19], 0, v[26:27]
	global_load_dwordx4 v[18:21], v[28:29], off
	v_cndmask_b32_e32 v23, v23, v25, vcc
	v_cndmask_b32_e32 v22, v22, v24, vcc
	v_lshl_add_u64 v[22:23], s[6:7], 0, v[22:23]
	v_lshl_add_u64 v[22:23], v[22:23], 0, v[26:27]
	global_load_dwordx4 v[174:177], v[28:29], off offset:64
	global_load_dwordx4 v[178:181], v[28:29], off offset:512
	global_load_dwordx4 v[182:185], v[28:29], off offset:576
	s_waitcnt vmcnt(3)
	v_pk_add_f32 v[16:17], v[16:17], v[20:21]
	v_pk_add_f32 v[14:15], v[14:15], v[18:19]
	global_store_dwordx4 v[22:23], v[14:17], off
	s_waitcnt vmcnt(3)
	v_pk_add_f32 v[12:13], v[12:13], v[176:177]
	v_pk_add_f32 v[10:11], v[10:11], v[174:175]
	global_store_dwordx4 v[22:23], v[10:13], off offset:64
	s_waitcnt vmcnt(3)
	v_pk_add_f32 v[8:9], v[8:9], v[180:181]
	v_pk_add_f32 v[6:7], v[6:7], v[178:179]
	global_store_dwordx4 v[22:23], v[6:9], off offset:512
	s_waitcnt vmcnt(3)
	v_pk_add_f32 v[4:5], v[4:5], v[184:185]
	v_pk_add_f32 v[2:3], v[2:3], v[182:183]
	global_store_dwordx4 v[22:23], v[2:5], off offset:576
